# v24 + in-proj gate epilogue re-emitted: bias loads and 1/rms LDS reads of a half in flight together, v_pk_fma_f32 / v_pk_mul_f32 on accumulator pairs (bit-identical)
# speedup vs baseline: 1.0138x; 1.0037x over previous
; __device__ __forceinline__ u32x4 pack8(const float (&v)[8]) { u32x4 w; w.x = pk2(v[0], v[1]); w.y = pk2(v[2], v[3]); w.z = pk2(v[4], v[5]); w.w = pk2(v[6], v[7]); return w; }
;     __device__ __forceinline__ bool operator()(Acc& acc, const Unit& u, int wr, int wc, int fr, int fq, const LAS float* rstab) const {
;     ...
;             if (colt >= C_G) {
;                 const int pl = (u.pn < 19) ? bj : 2, go = (u.pn < 19) ? (u.pn - 11) * HALF : colt - (C_G + 2048);
;                 bf16_t* p0 = Gt + (size_t)rowb * 3072 + pl * 1024 + go + cl;
;                 float bg[8];
;                 { const f32x4 b0 = gld<f32x4>(bgate + pl * 1024 + go + cl), b1 = gld<f32x4>(bgate + pl * 1024 + go + cl + 4);
; #pragma unroll
;                   for (int e = 0; e < 4; ++e) { bg[e] = -LOG2E * b0[e]; bg[4 + e] = -LOG2E * b1[e]; } }
; #pragma unroll
;                 for (int ai = 0; ai < 2; ++ai)
; #pragma unroll
;                     for (int m = 0; m < 4; ++m) {
;                         const float nrs = -LOG2E * rsp[ai * HALF + m * 16];
;                         float v[8];
; #pragma unroll
;                         for (int e = 0; e < 4; ++e) {
;                             v[e] = 1.0f + __builtin_amdgcn_exp2f(fminf(__builtin_fmaf(acc[ai][bj][m][0][e], nrs, bg[e]), 86.f));
;                             v[4 + e] = 1.0f + __builtin_amdgcn_exp2f(fminf(__builtin_fmaf(acc[ai][bj][m][1][e], nrs, bg[4 + e]), 86.f));
;                         }
;                         gst<u32x4>(p0 + (ai * HALF + m * 16) * 3072, pack8(v));
;                         asm volatile("" ::: "memory");
;                     }
.LBB0_422:
	s_movk_i32 s9, 0x1800
	s_and_b64 vcc, exec, s[14:15]
	v_readlane_b32 s14, v254, 57
	s_lshl_b32 s60, s70, 7
	v_mad_i64_i32 v[132:133], s[16:17], v2, s9, 0
	v_readlane_b32 s15, v254, 58
	s_addk_i32 s60, 0xfa80
	v_lshlrev_b32_e32 v159, 2, v155
	v_lshl_add_u64 v[140:141], s[14:15], 0, v[132:133]
	s_cbranch_vccz .LBB0_432
	s_add_i32 s9, s8, 0xffffed00
	s_and_b64 s[14:15], s[10:11], exec
	s_cselect_b32 s14, s60, s9
	s_cselect_b32 s9, 0, 0x800
	s_lshl_b32 s26, s9, 1
	s_ashr_i32 s15, s14, 31
	s_lshl_b32 s9, s9, 2
	v_lshl_add_u64 v[132:133], v[140:141], 0, s[26:27]
	s_add_u32 s9, s62, s9
	v_lshl_add_u64 v[142:143], s[14:15], 1, v[132:133]
	s_addc_u32 s16, s63, 0
	s_lshl_b64 s[14:15], s[14:15], 2
	s_add_u32 s14, s9, s14
	s_addc_u32 s15, s16, s15
	v_lshlrev_b32_e32 v0, 1, v155
	v_lshl_add_u64 v[142:143], v[142:143], 0, v[0:1]
	global_load_dwordx4 v[180:183], v159, s[14:15] offset:16
	global_load_dwordx4 v[176:179], v159, s[14:15]
	ds_read_b32 v184, v154
	ds_read_b32 v185, v154 offset:64
	ds_read_b32 v186, v154 offset:128
	ds_read_b32 v187, v154 offset:192
	ds_read_b32 v188, v154 offset:512
	ds_read_b32 v189, v154 offset:576
	ds_read_b32 v190, v154 offset:640
	ds_read_b32 v191, v154 offset:704
	v_mov_b32_e32 v192, 0xbfb8aa3b
	s_waitcnt vmcnt(0)
	v_pk_mul_f32 v[176:177], v[176:177], v[192:193] op_sel_hi:[1,0]
	v_pk_mul_f32 v[178:179], v[178:179], v[192:193] op_sel_hi:[1,0]
	v_pk_mul_f32 v[180:181], v[180:181], v[192:193] op_sel_hi:[1,0]
	v_pk_mul_f32 v[182:183], v[182:183], v[192:193] op_sel_hi:[1,0]
	s_waitcnt lgkmcnt(0)
	v_mul_f32_e32 v184, 0xbfb8aa3b, v184
	v_mul_f32_e32 v185, 0xbfb8aa3b, v185
	v_mul_f32_e32 v186, 0xbfb8aa3b, v186
	v_mul_f32_e32 v187, 0xbfb8aa3b, v187
	v_mul_f32_e32 v188, 0xbfb8aa3b, v188
	v_mul_f32_e32 v189, 0xbfb8aa3b, v189
	v_mul_f32_e32 v190, 0xbfb8aa3b, v190
	v_mul_f32_e32 v191, 0xbfb8aa3b, v191
	v_pk_fma_f32 v[208:209], v[120:121], v[184:185], v[176:177] op_sel_hi:[1,0,1]
	v_pk_fma_f32 v[210:211], v[122:123], v[184:185], v[178:179] op_sel_hi:[1,0,1]
	v_pk_fma_f32 v[212:213], v[112:113], v[184:185], v[180:181] op_sel_hi:[1,0,1]
	v_pk_fma_f32 v[214:215], v[114:115], v[184:185], v[182:183] op_sel_hi:[1,0,1]
	v_min_f32_e32 v208, 0x42ac0000, v208
	v_min_f32_e32 v209, 0x42ac0000, v209
	v_min_f32_e32 v210, 0x42ac0000, v210
	v_min_f32_e32 v211, 0x42ac0000, v211
	v_min_f32_e32 v212, 0x42ac0000, v212
	v_min_f32_e32 v213, 0x42ac0000, v213
	v_min_f32_e32 v214, 0x42ac0000, v214
	v_min_f32_e32 v215, 0x42ac0000, v215
	v_exp_f32_e32 v208, v208
	v_exp_f32_e32 v209, v209
	v_exp_f32_e32 v210, v210
	v_exp_f32_e32 v211, v211
	v_exp_f32_e32 v212, v212
	v_exp_f32_e32 v213, v213
	v_exp_f32_e32 v214, v214
	v_exp_f32_e32 v215, v215
	v_pk_add_f32 v[208:209], v[208:209], 1.0 op_sel_hi:[1,0]
	v_pk_add_f32 v[210:211], v[210:211], 1.0 op_sel_hi:[1,0]
	v_pk_add_f32 v[212:213], v[212:213], 1.0 op_sel_hi:[1,0]
	v_pk_add_f32 v[214:215], v[214:215], 1.0 op_sel_hi:[1,0]
	v_cvt_pk_bf16_f32 v132, v208, v209
	v_cvt_pk_bf16_f32 v133, v210, v211
	v_cvt_pk_bf16_f32 v134, v212, v213
	v_cvt_pk_bf16_f32 v135, v214, v215
	global_store_dwordx4 v[142:143], v[132:135], off
	v_pk_fma_f32 v[208:209], v[100:101], v[184:185], v[176:177] op_sel:[0,1,0] op_sel_hi:[1,1,1]
	v_pk_fma_f32 v[210:211], v[102:103], v[184:185], v[178:179] op_sel:[0,1,0] op_sel_hi:[1,1,1]
	v_pk_fma_f32 v[212:213], v[88:89], v[184:185], v[180:181] op_sel:[0,1,0] op_sel_hi:[1,1,1]
	v_pk_fma_f32 v[214:215], v[90:91], v[184:185], v[182:183] op_sel:[0,1,0] op_sel_hi:[1,1,1]
	v_min_f32_e32 v208, 0x42ac0000, v208
	v_min_f32_e32 v209, 0x42ac0000, v209
	v_min_f32_e32 v210, 0x42ac0000, v210
	v_min_f32_e32 v211, 0x42ac0000, v211
	v_min_f32_e32 v212, 0x42ac0000, v212
	v_min_f32_e32 v213, 0x42ac0000, v213
	v_min_f32_e32 v214, 0x42ac0000, v214
	v_min_f32_e32 v215, 0x42ac0000, v215
	v_exp_f32_e32 v208, v208
	v_exp_f32_e32 v209, v209
	v_exp_f32_e32 v210, v210
	v_exp_f32_e32 v211, v211
	v_exp_f32_e32 v212, v212
	v_exp_f32_e32 v213, v213
	v_exp_f32_e32 v214, v214
	v_exp_f32_e32 v215, v215
	v_pk_add_f32 v[208:209], v[208:209], 1.0 op_sel_hi:[1,0]
	v_pk_add_f32 v[210:211], v[210:211], 1.0 op_sel_hi:[1,0]
	v_pk_add_f32 v[212:213], v[212:213], 1.0 op_sel_hi:[1,0]
	v_pk_add_f32 v[214:215], v[214:215], 1.0 op_sel_hi:[1,0]
	v_cvt_pk_bf16_f32 v132, v208, v209
	v_cvt_pk_bf16_f32 v133, v210, v211
	v_cvt_pk_bf16_f32 v134, v212, v213
	v_cvt_pk_bf16_f32 v135, v214, v215
	v_add_co_u32_e32 v194, vcc, 0x18000, v142
	v_addc_co_u32_e32 v195, vcc, 0, v143, vcc
	global_store_dwordx4 v[194:195], v[132:135], off
	v_pk_fma_f32 v[208:209], v[68:69], v[186:187], v[176:177] op_sel_hi:[1,0,1]
	v_pk_fma_f32 v[210:211], v[70:71], v[186:187], v[178:179] op_sel_hi:[1,0,1]
	v_pk_fma_f32 v[212:213], v[56:57], v[186:187], v[180:181] op_sel_hi:[1,0,1]
	v_pk_fma_f32 v[214:215], v[58:59], v[186:187], v[182:183] op_sel_hi:[1,0,1]
	v_min_f32_e32 v208, 0x42ac0000, v208
	v_min_f32_e32 v209, 0x42ac0000, v209
	v_min_f32_e32 v210, 0x42ac0000, v210
	v_min_f32_e32 v211, 0x42ac0000, v211
	v_min_f32_e32 v212, 0x42ac0000, v212
	v_min_f32_e32 v213, 0x42ac0000, v213
	v_min_f32_e32 v214, 0x42ac0000, v214
	v_min_f32_e32 v215, 0x42ac0000, v215
	v_exp_f32_e32 v208, v208
	v_exp_f32_e32 v209, v209
	v_exp_f32_e32 v210, v210
	v_exp_f32_e32 v211, v211
	v_exp_f32_e32 v212, v212
	v_exp_f32_e32 v213, v213
	v_exp_f32_e32 v214, v214
	v_exp_f32_e32 v215, v215
	v_pk_add_f32 v[208:209], v[208:209], 1.0 op_sel_hi:[1,0]
	v_pk_add_f32 v[210:211], v[210:211], 1.0 op_sel_hi:[1,0]
	v_pk_add_f32 v[212:213], v[212:213], 1.0 op_sel_hi:[1,0]
	v_pk_add_f32 v[214:215], v[214:215], 1.0 op_sel_hi:[1,0]
	v_cvt_pk_bf16_f32 v132, v208, v209
	v_cvt_pk_bf16_f32 v133, v210, v211
; __device__ __forceinline__ u32x4 pack8(const float (&v)[8]) { u32x4 w; w.x = pk2(v[0], v[1]); w.y = pk2(v[2], v[3]); w.z = pk2(v[4], v[5]); w.w = pk2(v[6], v[7]); return w; }
;     __device__ __forceinline__ bool operator()(Acc& acc, const Unit& u, int wr, int wc, int fr, int fq, const LAS float* rstab) const {
;     ...
; #pragma unroll
;                 for (int ai = 0; ai < 2; ++ai)
; #pragma unroll
;                     for (int m = 0; m < 4; ++m) {
;                         const float nrs = -LOG2E * rsp[ai * HALF + m * 16];
;                         float v[8];
; #pragma unroll
;                         for (int e = 0; e < 4; ++e) {
;                             v[e] = 1.0f + __builtin_amdgcn_exp2f(fminf(__builtin_fmaf(acc[ai][bj][m][0][e], nrs, bg[e]), 86.f));
;                             v[4 + e] = 1.0f + __builtin_amdgcn_exp2f(fminf(__builtin_fmaf(acc[ai][bj][m][1][e], nrs, bg[4 + e]), 86.f));
;                         }
;                         gst<u32x4>(p0 + (ai * HALF + m * 16) * 3072, pack8(v));
;                         asm volatile("" ::: "memory");
;                     }
	v_cvt_pk_bf16_f32 v134, v212, v213
	v_cvt_pk_bf16_f32 v135, v214, v215
	v_add_co_u32_e32 v194, vcc, 0x30000, v142
	v_addc_co_u32_e32 v195, vcc, 0, v143, vcc
	global_store_dwordx4 v[194:195], v[132:135], off
	v_pk_fma_f32 v[208:209], v[36:37], v[186:187], v[176:177] op_sel:[0,1,0] op_sel_hi:[1,1,1]
	v_pk_fma_f32 v[210:211], v[38:39], v[186:187], v[178:179] op_sel:[0,1,0] op_sel_hi:[1,1,1]
	v_pk_fma_f32 v[212:213], v[28:29], v[186:187], v[180:181] op_sel:[0,1,0] op_sel_hi:[1,1,1]
	v_pk_fma_f32 v[214:215], v[30:31], v[186:187], v[182:183] op_sel:[0,1,0] op_sel_hi:[1,1,1]
	v_min_f32_e32 v208, 0x42ac0000, v208
	v_min_f32_e32 v209, 0x42ac0000, v209
	v_min_f32_e32 v210, 0x42ac0000, v210
	v_min_f32_e32 v211, 0x42ac0000, v211
	v_min_f32_e32 v212, 0x42ac0000, v212
	v_min_f32_e32 v213, 0x42ac0000, v213
	v_min_f32_e32 v214, 0x42ac0000, v214
	v_min_f32_e32 v215, 0x42ac0000, v215
	v_exp_f32_e32 v208, v208
	v_exp_f32_e32 v209, v209
	v_exp_f32_e32 v210, v210
	v_exp_f32_e32 v211, v211
	v_exp_f32_e32 v212, v212
	v_exp_f32_e32 v213, v213
	v_exp_f32_e32 v214, v214
	v_exp_f32_e32 v215, v215
	v_pk_add_f32 v[208:209], v[208:209], 1.0 op_sel_hi:[1,0]
	v_pk_add_f32 v[210:211], v[210:211], 1.0 op_sel_hi:[1,0]
	v_pk_add_f32 v[212:213], v[212:213], 1.0 op_sel_hi:[1,0]
	v_pk_add_f32 v[214:215], v[214:215], 1.0 op_sel_hi:[1,0]
	v_cvt_pk_bf16_f32 v132, v208, v209
	v_cvt_pk_bf16_f32 v133, v210, v211
	v_cvt_pk_bf16_f32 v134, v212, v213
	v_cvt_pk_bf16_f32 v135, v214, v215
	v_add_co_u32_e32 v194, vcc, 0x48000, v142
	v_addc_co_u32_e32 v195, vcc, 0, v143, vcc
	global_store_dwordx4 v[194:195], v[132:135], off
	v_pk_fma_f32 v[208:209], v[72:73], v[188:189], v[176:177] op_sel_hi:[1,0,1]
	v_pk_fma_f32 v[210:211], v[74:75], v[188:189], v[178:179] op_sel_hi:[1,0,1]
	v_pk_fma_f32 v[212:213], v[60:61], v[188:189], v[180:181] op_sel_hi:[1,0,1]
	v_pk_fma_f32 v[214:215], v[62:63], v[188:189], v[182:183] op_sel_hi:[1,0,1]
	v_min_f32_e32 v208, 0x42ac0000, v208
	v_min_f32_e32 v209, 0x42ac0000, v209
	v_min_f32_e32 v210, 0x42ac0000, v210
	v_min_f32_e32 v211, 0x42ac0000, v211
	v_min_f32_e32 v212, 0x42ac0000, v212
	v_min_f32_e32 v213, 0x42ac0000, v213
	v_min_f32_e32 v214, 0x42ac0000, v214
	v_min_f32_e32 v215, 0x42ac0000, v215
	v_exp_f32_e32 v208, v208
	v_exp_f32_e32 v209, v209
	v_exp_f32_e32 v210, v210
	v_exp_f32_e32 v211, v211
	v_exp_f32_e32 v212, v212
	v_exp_f32_e32 v213, v213
	v_exp_f32_e32 v214, v214
	v_exp_f32_e32 v215, v215
	v_pk_add_f32 v[208:209], v[208:209], 1.0 op_sel_hi:[1,0]
	v_pk_add_f32 v[210:211], v[210:211], 1.0 op_sel_hi:[1,0]
	v_pk_add_f32 v[212:213], v[212:213], 1.0 op_sel_hi:[1,0]
	v_pk_add_f32 v[214:215], v[214:215], 1.0 op_sel_hi:[1,0]
	v_cvt_pk_bf16_f32 v132, v208, v209
	v_cvt_pk_bf16_f32 v133, v210, v211
	v_cvt_pk_bf16_f32 v134, v212, v213
	v_cvt_pk_bf16_f32 v135, v214, v215
	v_add_co_u32_e32 v194, vcc, 0xc0000, v142
	v_addc_co_u32_e32 v195, vcc, 0, v143, vcc
	global_store_dwordx4 v[194:195], v[132:135], off
	v_pk_fma_f32 v[208:209], v[40:41], v[188:189], v[176:177] op_sel:[0,1,0] op_sel_hi:[1,1,1]
	v_pk_fma_f32 v[210:211], v[42:43], v[188:189], v[178:179] op_sel:[0,1,0] op_sel_hi:[1,1,1]
	v_pk_fma_f32 v[212:213], v[32:33], v[188:189], v[180:181] op_sel:[0,1,0] op_sel_hi:[1,1,1]
	v_pk_fma_f32 v[214:215], v[34:35], v[188:189], v[182:183] op_sel:[0,1,0] op_sel_hi:[1,1,1]
	v_min_f32_e32 v208, 0x42ac0000, v208
	v_min_f32_e32 v209, 0x42ac0000, v209
	v_min_f32_e32 v210, 0x42ac0000, v210
	v_min_f32_e32 v211, 0x42ac0000, v211
	v_min_f32_e32 v212, 0x42ac0000, v212
	v_min_f32_e32 v213, 0x42ac0000, v213
	v_min_f32_e32 v214, 0x42ac0000, v214
	v_min_f32_e32 v215, 0x42ac0000, v215
	v_exp_f32_e32 v208, v208
	v_exp_f32_e32 v209, v209
	v_exp_f32_e32 v210, v210
	v_exp_f32_e32 v211, v211
	v_exp_f32_e32 v212, v212
	v_exp_f32_e32 v213, v213
	v_exp_f32_e32 v214, v214
	v_exp_f32_e32 v215, v215
	v_pk_add_f32 v[208:209], v[208:209], 1.0 op_sel_hi:[1,0]
	v_pk_add_f32 v[210:211], v[210:211], 1.0 op_sel_hi:[1,0]
	v_pk_add_f32 v[212:213], v[212:213], 1.0 op_sel_hi:[1,0]
	v_pk_add_f32 v[214:215], v[214:215], 1.0 op_sel_hi:[1,0]
	v_cvt_pk_bf16_f32 v132, v208, v209
	v_cvt_pk_bf16_f32 v133, v210, v211
	v_cvt_pk_bf16_f32 v134, v212, v213
	v_cvt_pk_bf16_f32 v135, v214, v215
	v_add_co_u32_e32 v194, vcc, 0xd8000, v142
	v_addc_co_u32_e32 v195, vcc, 0, v143, vcc
	global_store_dwordx4 v[194:195], v[132:135], off
	v_pk_fma_f32 v[208:209], v[16:17], v[190:191], v[176:177] op_sel_hi:[1,0,1]
	v_pk_fma_f32 v[210:211], v[18:19], v[190:191], v[178:179] op_sel_hi:[1,0,1]
	v_pk_fma_f32 v[212:213], v[12:13], v[190:191], v[180:181] op_sel_hi:[1,0,1]
	v_pk_fma_f32 v[214:215], v[14:15], v[190:191], v[182:183] op_sel_hi:[1,0,1]
	v_min_f32_e32 v208, 0x42ac0000, v208
	v_min_f32_e32 v209, 0x42ac0000, v209
	v_min_f32_e32 v210, 0x42ac0000, v210
	v_min_f32_e32 v211, 0x42ac0000, v211
	v_min_f32_e32 v212, 0x42ac0000, v212
	v_min_f32_e32 v213, 0x42ac0000, v213
	v_min_f32_e32 v214, 0x42ac0000, v214
	v_min_f32_e32 v215, 0x42ac0000, v215
	v_exp_f32_e32 v208, v208
	v_exp_f32_e32 v209, v209
	v_exp_f32_e32 v210, v210
	v_exp_f32_e32 v211, v211
	v_exp_f32_e32 v212, v212
	v_exp_f32_e32 v213, v213
	v_exp_f32_e32 v214, v214
	v_exp_f32_e32 v215, v215
	v_pk_add_f32 v[208:209], v[208:209], 1.0 op_sel_hi:[1,0]
	v_pk_add_f32 v[210:211], v[210:211], 1.0 op_sel_hi:[1,0]
	v_pk_add_f32 v[212:213], v[212:213], 1.0 op_sel_hi:[1,0]
	v_pk_add_f32 v[214:215], v[214:215], 1.0 op_sel_hi:[1,0]
	v_cvt_pk_bf16_f32 v132, v208, v209
	v_cvt_pk_bf16_f32 v133, v210, v211
	v_cvt_pk_bf16_f32 v134, v212, v213
	v_cvt_pk_bf16_f32 v135, v214, v215
	v_add_co_u32_e32 v194, vcc, 0xf0000, v142
	v_addc_co_u32_e32 v195, vcc, 0, v143, vcc
	global_store_dwordx4 v[194:195], v[132:135], off
; __device__ __forceinline__ u32x4 pack8(const float (&v)[8]) { u32x4 w; w.x = pk2(v[0], v[1]); w.y = pk2(v[2], v[3]); w.z = pk2(v[4], v[5]); w.w = pk2(v[6], v[7]); return w; }
;     __device__ __forceinline__ bool operator()(Acc& acc, const Unit& u, int wr, int wc, int fr, int fq, const LAS float* rstab) const {
;     ...
;                 const int pl = (u.pn < 19) ? bj : 2, go = (u.pn < 19) ? (u.pn - 11) * HALF : colt - (C_G + 2048);
;                 bf16_t* p0 = Gt + (size_t)rowb * 3072 + pl * 1024 + go + cl;
;                 float bg[8];
;                 { const f32x4 b0 = gld<f32x4>(bgate + pl * 1024 + go + cl), b1 = gld<f32x4>(bgate + pl * 1024 + go + cl + 4);
; #pragma unroll
;                   for (int e = 0; e < 4; ++e) { bg[e] = -LOG2E * b0[e]; bg[4 + e] = -LOG2E * b1[e]; } }
; #pragma unroll
;                 for (int ai = 0; ai < 2; ++ai)
; #pragma unroll
;                     for (int m = 0; m < 4; ++m) {
;                         const float nrs = -LOG2E * rsp[ai * HALF + m * 16];
;                         float v[8];
; #pragma unroll
;                         for (int e = 0; e < 4; ++e) {
;                             v[e] = 1.0f + __builtin_amdgcn_exp2f(fminf(__builtin_fmaf(acc[ai][bj][m][0][e], nrs, bg[e]), 86.f));
;                             v[4 + e] = 1.0f + __builtin_amdgcn_exp2f(fminf(__builtin_fmaf(acc[ai][bj][m][1][e], nrs, bg[4 + e]), 86.f));
;                         }
;                         gst<u32x4>(p0 + (ai * HALF + m * 16) * 3072, pack8(v));
;                         asm volatile("" ::: "memory");
;                     }
	v_pk_fma_f32 v[208:209], v[8:9], v[190:191], v[176:177] op_sel:[0,1,0] op_sel_hi:[1,1,1]
	v_pk_fma_f32 v[210:211], v[10:11], v[190:191], v[178:179] op_sel:[0,1,0] op_sel_hi:[1,1,1]
	v_pk_fma_f32 v[212:213], v[4:5], v[190:191], v[180:181] op_sel:[0,1,0] op_sel_hi:[1,1,1]
	v_pk_fma_f32 v[214:215], v[6:7], v[190:191], v[182:183] op_sel:[0,1,0] op_sel_hi:[1,1,1]
	v_min_f32_e32 v208, 0x42ac0000, v208
	v_min_f32_e32 v209, 0x42ac0000, v209
	v_min_f32_e32 v210, 0x42ac0000, v210
	v_min_f32_e32 v211, 0x42ac0000, v211
	v_min_f32_e32 v212, 0x42ac0000, v212
	v_min_f32_e32 v213, 0x42ac0000, v213
	v_min_f32_e32 v214, 0x42ac0000, v214
	v_min_f32_e32 v215, 0x42ac0000, v215
	v_exp_f32_e32 v208, v208
	v_exp_f32_e32 v209, v209
	v_exp_f32_e32 v210, v210
	v_exp_f32_e32 v211, v211
	v_exp_f32_e32 v212, v212
	v_exp_f32_e32 v213, v213
	v_exp_f32_e32 v214, v214
	v_exp_f32_e32 v215, v215
	v_pk_add_f32 v[208:209], v[208:209], 1.0 op_sel_hi:[1,0]
	v_pk_add_f32 v[210:211], v[210:211], 1.0 op_sel_hi:[1,0]
	v_pk_add_f32 v[212:213], v[212:213], 1.0 op_sel_hi:[1,0]
	v_pk_add_f32 v[214:215], v[214:215], 1.0 op_sel_hi:[1,0]
	v_cvt_pk_bf16_f32 v132, v208, v209
	v_cvt_pk_bf16_f32 v133, v210, v211
	v_cvt_pk_bf16_f32 v134, v212, v213
	v_cvt_pk_bf16_f32 v135, v214, v215
	v_add_co_u32_e32 v142, vcc, 0x108000, v142
	v_addc_co_u32_e32 v143, vcc, 0, v143, vcc
	global_store_dwordx4 v[142:143], v[132:135], off
	s_or_b32 s9, s8, 0x80
	s_cmpk_gt_i32 s9, 0xaff
	s_mov_b64 s[14:15], -1
	s_cbranch_scc0 .LBB0_433
.LBB0_424:
	s_and_b64 vcc, exec, s[14:15]
	s_cbranch_vccz .LBB0_426
	s_add_i32 s12, s8, 0xffffed80
	s_and_b64 s[8:9], s[10:11], exec
	s_movk_i32 s9, 0x800
	s_cselect_b32 s8, s60, s12
	s_cselect_b32 s10, 0x400, s9
	s_lshl_b32 s26, s10, 1
	s_ashr_i32 s9, s8, 31
	s_lshl_b32 s10, s10, 2
	v_lshl_add_u64 v[132:133], v[140:141], 0, s[26:27]
	s_add_u32 s10, s62, s10
	v_lshl_add_u64 v[160:161], s[8:9], 1, v[132:133]
	s_addc_u32 s11, s63, 0
	s_lshl_b64 s[8:9], s[8:9], 2
	s_add_u32 s8, s10, s8
	s_addc_u32 s9, s11, s9
	v_lshlrev_b32_e32 v0, 1, v155
	v_lshl_add_u64 v[136:137], v[160:161], 0, v[0:1]
	global_load_dwordx4 v[180:183], v159, s[8:9] offset:16
	global_load_dwordx4 v[176:179], v159, s[8:9]
	ds_read_b32 v184, v154
	ds_read_b32 v185, v154 offset:64
	ds_read_b32 v186, v154 offset:128
	ds_read_b32 v187, v154 offset:192
	ds_read_b32 v188, v154 offset:512
	ds_read_b32 v189, v154 offset:576
	ds_read_b32 v190, v154 offset:640
	ds_read_b32 v191, v154 offset:704
	v_mov_b32_e32 v192, 0xbfb8aa3b
	s_waitcnt vmcnt(0)
	v_pk_mul_f32 v[176:177], v[176:177], v[192:193] op_sel_hi:[1,0]
	v_pk_mul_f32 v[178:179], v[178:179], v[192:193] op_sel_hi:[1,0]
	v_pk_mul_f32 v[180:181], v[180:181], v[192:193] op_sel_hi:[1,0]
	v_pk_mul_f32 v[182:183], v[182:183], v[192:193] op_sel_hi:[1,0]
	s_waitcnt lgkmcnt(0)
	v_mul_f32_e32 v184, 0xbfb8aa3b, v184
	v_mul_f32_e32 v185, 0xbfb8aa3b, v185
	v_mul_f32_e32 v186, 0xbfb8aa3b, v186
	v_mul_f32_e32 v187, 0xbfb8aa3b, v187
	v_mul_f32_e32 v188, 0xbfb8aa3b, v188
	v_mul_f32_e32 v189, 0xbfb8aa3b, v189
	v_mul_f32_e32 v190, 0xbfb8aa3b, v190
	v_mul_f32_e32 v191, 0xbfb8aa3b, v191
	v_pk_fma_f32 v[208:209], v[128:129], v[184:185], v[176:177] op_sel_hi:[1,0,1]
	v_pk_fma_f32 v[210:211], v[130:131], v[184:185], v[178:179] op_sel_hi:[1,0,1]
	v_pk_fma_f32 v[212:213], v[124:125], v[184:185], v[180:181] op_sel_hi:[1,0,1]
	v_pk_fma_f32 v[214:215], v[126:127], v[184:185], v[182:183] op_sel_hi:[1,0,1]
	v_min_f32_e32 v208, 0x42ac0000, v208
	v_min_f32_e32 v209, 0x42ac0000, v209
	v_min_f32_e32 v210, 0x42ac0000, v210
	v_min_f32_e32 v211, 0x42ac0000, v211
	v_min_f32_e32 v212, 0x42ac0000, v212
	v_min_f32_e32 v213, 0x42ac0000, v213
	v_min_f32_e32 v214, 0x42ac0000, v214
	v_min_f32_e32 v215, 0x42ac0000, v215
	v_exp_f32_e32 v208, v208
	v_exp_f32_e32 v209, v209
	v_exp_f32_e32 v210, v210
	v_exp_f32_e32 v211, v211
	v_exp_f32_e32 v212, v212
	v_exp_f32_e32 v213, v213
	v_exp_f32_e32 v214, v214
	v_exp_f32_e32 v215, v215
	v_pk_add_f32 v[208:209], v[208:209], 1.0 op_sel_hi:[1,0]
	v_pk_add_f32 v[210:211], v[210:211], 1.0 op_sel_hi:[1,0]
	v_pk_add_f32 v[212:213], v[212:213], 1.0 op_sel_hi:[1,0]
	v_pk_add_f32 v[214:215], v[214:215], 1.0 op_sel_hi:[1,0]
	v_cvt_pk_bf16_f32 v132, v208, v209
	v_cvt_pk_bf16_f32 v133, v210, v211
	v_cvt_pk_bf16_f32 v134, v212, v213
	v_cvt_pk_bf16_f32 v135, v214, v215
	global_store_dwordx4 v[136:137], v[132:135], off
	v_pk_fma_f32 v[208:209], v[116:117], v[184:185], v[176:177] op_sel:[0,1,0] op_sel_hi:[1,1,1]
	v_pk_fma_f32 v[210:211], v[118:119], v[184:185], v[178:179] op_sel:[0,1,0] op_sel_hi:[1,1,1]
	v_pk_fma_f32 v[212:213], v[108:109], v[184:185], v[180:181] op_sel:[0,1,0] op_sel_hi:[1,1,1]
	v_pk_fma_f32 v[214:215], v[110:111], v[184:185], v[182:183] op_sel:[0,1,0] op_sel_hi:[1,1,1]
	v_min_f32_e32 v208, 0x42ac0000, v208
	v_min_f32_e32 v209, 0x42ac0000, v209
	v_min_f32_e32 v210, 0x42ac0000, v210
	v_min_f32_e32 v211, 0x42ac0000, v211
	v_min_f32_e32 v212, 0x42ac0000, v212
	v_min_f32_e32 v213, 0x42ac0000, v213
	v_min_f32_e32 v214, 0x42ac0000, v214
	v_min_f32_e32 v215, 0x42ac0000, v215
	v_exp_f32_e32 v208, v208
	v_exp_f32_e32 v209, v209
	v_exp_f32_e32 v210, v210
	v_exp_f32_e32 v211, v211
	v_exp_f32_e32 v212, v212
	v_exp_f32_e32 v213, v213
	v_exp_f32_e32 v214, v214
	v_exp_f32_e32 v215, v215
	v_pk_add_f32 v[208:209], v[208:209], 1.0 op_sel_hi:[1,0]
	v_pk_add_f32 v[210:211], v[210:211], 1.0 op_sel_hi:[1,0]
	v_pk_add_f32 v[212:213], v[212:213], 1.0 op_sel_hi:[1,0]
	v_pk_add_f32 v[214:215], v[214:215], 1.0 op_sel_hi:[1,0]
	v_cvt_pk_bf16_f32 v132, v208, v209
	v_cvt_pk_bf16_f32 v133, v210, v211
	v_cvt_pk_bf16_f32 v134, v212, v213
	v_cvt_pk_bf16_f32 v135, v214, v215
	v_add_co_u32_e32 v194, vcc, 0x18000, v136
; __device__ __forceinline__ u32x4 pack8(const float (&v)[8]) { u32x4 w; w.x = pk2(v[0], v[1]); w.y = pk2(v[2], v[3]); w.z = pk2(v[4], v[5]); w.w = pk2(v[6], v[7]); return w; }
;     __device__ __forceinline__ bool operator()(Acc& acc, const Unit& u, int wr, int wc, int fr, int fq, const LAS float* rstab) const {
;     ...
; #pragma unroll
;                 for (int ai = 0; ai < 2; ++ai)
; #pragma unroll
;                     for (int m = 0; m < 4; ++m) {
;                         const float nrs = -LOG2E * rsp[ai * HALF + m * 16];
;                         float v[8];
; #pragma unroll
;                         for (int e = 0; e < 4; ++e) {
;                             v[e] = 1.0f + __builtin_amdgcn_exp2f(fminf(__builtin_fmaf(acc[ai][bj][m][0][e], nrs, bg[e]), 86.f));
;                             v[4 + e] = 1.0f + __builtin_amdgcn_exp2f(fminf(__builtin_fmaf(acc[ai][bj][m][1][e], nrs, bg[4 + e]), 86.f));
;                         }
;                         gst<u32x4>(p0 + (ai * HALF + m * 16) * 3072, pack8(v));
;                         asm volatile("" ::: "memory");
;                     }
	v_addc_co_u32_e32 v195, vcc, 0, v137, vcc
	global_store_dwordx4 v[194:195], v[132:135], off
	v_pk_fma_f32 v[208:209], v[92:93], v[186:187], v[176:177] op_sel_hi:[1,0,1]
	v_pk_fma_f32 v[210:211], v[94:95], v[186:187], v[178:179] op_sel_hi:[1,0,1]
	v_pk_fma_f32 v[212:213], v[80:81], v[186:187], v[180:181] op_sel_hi:[1,0,1]
	v_pk_fma_f32 v[214:215], v[82:83], v[186:187], v[182:183] op_sel_hi:[1,0,1]
	v_min_f32_e32 v208, 0x42ac0000, v208
	v_min_f32_e32 v209, 0x42ac0000, v209
	v_min_f32_e32 v210, 0x42ac0000, v210
	v_min_f32_e32 v211, 0x42ac0000, v211
	v_min_f32_e32 v212, 0x42ac0000, v212
	v_min_f32_e32 v213, 0x42ac0000, v213
	v_min_f32_e32 v214, 0x42ac0000, v214
	v_min_f32_e32 v215, 0x42ac0000, v215
	v_exp_f32_e32 v208, v208
	v_exp_f32_e32 v209, v209
	v_exp_f32_e32 v210, v210
	v_exp_f32_e32 v211, v211
	v_exp_f32_e32 v212, v212
	v_exp_f32_e32 v213, v213
	v_exp_f32_e32 v214, v214
	v_exp_f32_e32 v215, v215
	v_pk_add_f32 v[208:209], v[208:209], 1.0 op_sel_hi:[1,0]
	v_pk_add_f32 v[210:211], v[210:211], 1.0 op_sel_hi:[1,0]
	v_pk_add_f32 v[212:213], v[212:213], 1.0 op_sel_hi:[1,0]
	v_pk_add_f32 v[214:215], v[214:215], 1.0 op_sel_hi:[1,0]
	v_cvt_pk_bf16_f32 v132, v208, v209
	v_cvt_pk_bf16_f32 v133, v210, v211
	v_cvt_pk_bf16_f32 v134, v212, v213
	v_cvt_pk_bf16_f32 v135, v214, v215
	v_add_co_u32_e32 v194, vcc, 0x30000, v136
	v_addc_co_u32_e32 v195, vcc, 0, v137, vcc
	global_store_dwordx4 v[194:195], v[132:135], off
	v_pk_fma_f32 v[208:209], v[64:65], v[186:187], v[176:177] op_sel:[0,1,0] op_sel_hi:[1,1,1]
	v_pk_fma_f32 v[210:211], v[66:67], v[186:187], v[178:179] op_sel:[0,1,0] op_sel_hi:[1,1,1]
	v_pk_fma_f32 v[212:213], v[48:49], v[186:187], v[180:181] op_sel:[0,1,0] op_sel_hi:[1,1,1]
	v_pk_fma_f32 v[214:215], v[50:51], v[186:187], v[182:183] op_sel:[0,1,0] op_sel_hi:[1,1,1]
	v_min_f32_e32 v208, 0x42ac0000, v208
	v_min_f32_e32 v209, 0x42ac0000, v209
	v_min_f32_e32 v210, 0x42ac0000, v210
	v_min_f32_e32 v211, 0x42ac0000, v211
	v_min_f32_e32 v212, 0x42ac0000, v212
	v_min_f32_e32 v213, 0x42ac0000, v213
	v_min_f32_e32 v214, 0x42ac0000, v214
	v_min_f32_e32 v215, 0x42ac0000, v215
	v_exp_f32_e32 v208, v208
	v_exp_f32_e32 v209, v209
	v_exp_f32_e32 v210, v210
	v_exp_f32_e32 v211, v211
	v_exp_f32_e32 v212, v212
	v_exp_f32_e32 v213, v213
	v_exp_f32_e32 v214, v214
	v_exp_f32_e32 v215, v215
	v_pk_add_f32 v[208:209], v[208:209], 1.0 op_sel_hi:[1,0]
	v_pk_add_f32 v[210:211], v[210:211], 1.0 op_sel_hi:[1,0]
	v_pk_add_f32 v[212:213], v[212:213], 1.0 op_sel_hi:[1,0]
	v_pk_add_f32 v[214:215], v[214:215], 1.0 op_sel_hi:[1,0]
	v_cvt_pk_bf16_f32 v132, v208, v209
	v_cvt_pk_bf16_f32 v133, v210, v211
	v_cvt_pk_bf16_f32 v134, v212, v213
	v_cvt_pk_bf16_f32 v135, v214, v215
	v_add_co_u32_e32 v194, vcc, 0x48000, v136
	v_addc_co_u32_e32 v195, vcc, 0, v137, vcc
	global_store_dwordx4 v[194:195], v[132:135], off
	v_pk_fma_f32 v[208:209], v[96:97], v[188:189], v[176:177] op_sel_hi:[1,0,1]
	v_pk_fma_f32 v[210:211], v[98:99], v[188:189], v[178:179] op_sel_hi:[1,0,1]
	v_pk_fma_f32 v[212:213], v[104:105], v[188:189], v[180:181] op_sel_hi:[1,0,1]
	v_pk_fma_f32 v[214:215], v[106:107], v[188:189], v[182:183] op_sel_hi:[1,0,1]
	v_min_f32_e32 v208, 0x42ac0000, v208
	v_min_f32_e32 v209, 0x42ac0000, v209
	v_min_f32_e32 v210, 0x42ac0000, v210
	v_min_f32_e32 v211, 0x42ac0000, v211
	v_min_f32_e32 v212, 0x42ac0000, v212
	v_min_f32_e32 v213, 0x42ac0000, v213
	v_min_f32_e32 v214, 0x42ac0000, v214
	v_min_f32_e32 v215, 0x42ac0000, v215
	v_exp_f32_e32 v208, v208
	v_exp_f32_e32 v209, v209
	v_exp_f32_e32 v210, v210
	v_exp_f32_e32 v211, v211
	v_exp_f32_e32 v212, v212
	v_exp_f32_e32 v213, v213
	v_exp_f32_e32 v214, v214
	v_exp_f32_e32 v215, v215
	v_pk_add_f32 v[208:209], v[208:209], 1.0 op_sel_hi:[1,0]
	v_pk_add_f32 v[210:211], v[210:211], 1.0 op_sel_hi:[1,0]
	v_pk_add_f32 v[212:213], v[212:213], 1.0 op_sel_hi:[1,0]
	v_pk_add_f32 v[214:215], v[214:215], 1.0 op_sel_hi:[1,0]
	v_cvt_pk_bf16_f32 v132, v208, v209
	v_cvt_pk_bf16_f32 v133, v210, v211
	v_cvt_pk_bf16_f32 v134, v212, v213
	v_cvt_pk_bf16_f32 v135, v214, v215
	v_add_co_u32_e32 v194, vcc, 0xc0000, v136
	v_addc_co_u32_e32 v195, vcc, 0, v137, vcc
	global_store_dwordx4 v[194:195], v[132:135], off
; __device__ __forceinline__ u32x4 pack8(const float (&v)[8]) { u32x4 w; w.x = pk2(v[0], v[1]); w.y = pk2(v[2], v[3]); w.z = pk2(v[4], v[5]); w.w = pk2(v[6], v[7]); return w; }
;     __device__ __forceinline__ bool operator()(Acc& acc, const Unit& u, int wr, int wc, int fr, int fq, const LAS float* rstab) const {
;     ...
; #pragma unroll
;                 for (int ai = 0; ai < 2; ++ai)
; #pragma unroll
;                     for (int m = 0; m < 4; ++m) {
;                         const float nrs = -LOG2E * rsp[ai * HALF + m * 16];
;                         float v[8];
; #pragma unroll
;                         for (int e = 0; e < 4; ++e) {
;                             v[e] = 1.0f + __builtin_amdgcn_exp2f(fminf(__builtin_fmaf(acc[ai][bj][m][0][e], nrs, bg[e]), 86.f));
;                             v[4 + e] = 1.0f + __builtin_amdgcn_exp2f(fminf(__builtin_fmaf(acc[ai][bj][m][1][e], nrs, bg[4 + e]), 86.f));
;                         }
;                         gst<u32x4>(p0 + (ai * HALF + m * 16) * 3072, pack8(v));
;                         asm volatile("" ::: "memory");
;                     }
	v_pk_fma_f32 v[208:209], v[84:85], v[188:189], v[176:177] op_sel:[0,1,0] op_sel_hi:[1,1,1]
	v_pk_fma_f32 v[210:211], v[86:87], v[188:189], v[178:179] op_sel:[0,1,0] op_sel_hi:[1,1,1]
	v_pk_fma_f32 v[212:213], v[76:77], v[188:189], v[180:181] op_sel:[0,1,0] op_sel_hi:[1,1,1]
	v_pk_fma_f32 v[214:215], v[78:79], v[188:189], v[182:183] op_sel:[0,1,0] op_sel_hi:[1,1,1]
	v_min_f32_e32 v208, 0x42ac0000, v208
	v_min_f32_e32 v209, 0x42ac0000, v209
	v_min_f32_e32 v210, 0x42ac0000, v210
	v_min_f32_e32 v211, 0x42ac0000, v211
	v_min_f32_e32 v212, 0x42ac0000, v212
	v_min_f32_e32 v213, 0x42ac0000, v213
	v_min_f32_e32 v214, 0x42ac0000, v214
	v_min_f32_e32 v215, 0x42ac0000, v215
	v_exp_f32_e32 v208, v208
	v_exp_f32_e32 v209, v209
	v_exp_f32_e32 v210, v210
	v_exp_f32_e32 v211, v211
	v_exp_f32_e32 v212, v212
	v_exp_f32_e32 v213, v213
	v_exp_f32_e32 v214, v214
	v_exp_f32_e32 v215, v215
	v_pk_add_f32 v[208:209], v[208:209], 1.0 op_sel_hi:[1,0]
	v_pk_add_f32 v[210:211], v[210:211], 1.0 op_sel_hi:[1,0]
	v_pk_add_f32 v[212:213], v[212:213], 1.0 op_sel_hi:[1,0]
	v_pk_add_f32 v[214:215], v[214:215], 1.0 op_sel_hi:[1,0]
	v_cvt_pk_bf16_f32 v132, v208, v209
	v_cvt_pk_bf16_f32 v133, v210, v211
	v_cvt_pk_bf16_f32 v134, v212, v213
	v_cvt_pk_bf16_f32 v135, v214, v215
	v_add_co_u32_e32 v194, vcc, 0xd8000, v136
	v_addc_co_u32_e32 v195, vcc, 0, v137, vcc
	global_store_dwordx4 v[194:195], v[132:135], off
	v_pk_fma_f32 v[208:209], v[52:53], v[190:191], v[176:177] op_sel_hi:[1,0,1]
	v_pk_fma_f32 v[210:211], v[54:55], v[190:191], v[178:179] op_sel_hi:[1,0,1]
	v_pk_fma_f32 v[212:213], v[44:45], v[190:191], v[180:181] op_sel_hi:[1,0,1]
	v_pk_fma_f32 v[214:215], v[46:47], v[190:191], v[182:183] op_sel_hi:[1,0,1]
	v_min_f32_e32 v208, 0x42ac0000, v208
	v_min_f32_e32 v209, 0x42ac0000, v209
	v_min_f32_e32 v210, 0x42ac0000, v210
	v_min_f32_e32 v211, 0x42ac0000, v211
	v_min_f32_e32 v212, 0x42ac0000, v212
	v_min_f32_e32 v213, 0x42ac0000, v213
	v_min_f32_e32 v214, 0x42ac0000, v214
	v_min_f32_e32 v215, 0x42ac0000, v215
	v_exp_f32_e32 v208, v208
	v_exp_f32_e32 v209, v209
	v_exp_f32_e32 v210, v210
	v_exp_f32_e32 v211, v211
	v_exp_f32_e32 v212, v212
	v_exp_f32_e32 v213, v213
	v_exp_f32_e32 v214, v214
	v_exp_f32_e32 v215, v215
	v_pk_add_f32 v[208:209], v[208:209], 1.0 op_sel_hi:[1,0]
	v_pk_add_f32 v[210:211], v[210:211], 1.0 op_sel_hi:[1,0]
	v_pk_add_f32 v[212:213], v[212:213], 1.0 op_sel_hi:[1,0]
	v_pk_add_f32 v[214:215], v[214:215], 1.0 op_sel_hi:[1,0]
	v_cvt_pk_bf16_f32 v132, v208, v209
	v_cvt_pk_bf16_f32 v133, v210, v211
	v_cvt_pk_bf16_f32 v134, v212, v213
	v_cvt_pk_bf16_f32 v135, v214, v215
	v_add_co_u32_e32 v194, vcc, 0xf0000, v136
	v_addc_co_u32_e32 v195, vcc, 0, v137, vcc
	global_store_dwordx4 v[194:195], v[132:135], off
	v_pk_fma_f32 v[208:209], v[24:25], v[190:191], v[176:177] op_sel:[0,1,0] op_sel_hi:[1,1,1]
	v_pk_fma_f32 v[210:211], v[26:27], v[190:191], v[178:179] op_sel:[0,1,0] op_sel_hi:[1,1,1]
	v_pk_fma_f32 v[212:213], v[20:21], v[190:191], v[180:181] op_sel:[0,1,0] op_sel_hi:[1,1,1]
	v_pk_fma_f32 v[214:215], v[22:23], v[190:191], v[182:183] op_sel:[0,1,0] op_sel_hi:[1,1,1]
	v_min_f32_e32 v208, 0x42ac0000, v208
	v_min_f32_e32 v209, 0x42ac0000, v209
	v_min_f32_e32 v210, 0x42ac0000, v210
	v_min_f32_e32 v211, 0x42ac0000, v211
	v_min_f32_e32 v212, 0x42ac0000, v212
	v_min_f32_e32 v213, 0x42ac0000, v213
	v_min_f32_e32 v214, 0x42ac0000, v214
	v_min_f32_e32 v215, 0x42ac0000, v215
	v_exp_f32_e32 v208, v208
	v_exp_f32_e32 v209, v209
	v_exp_f32_e32 v210, v210
	v_exp_f32_e32 v211, v211
	v_exp_f32_e32 v212, v212
	v_exp_f32_e32 v213, v213
	v_exp_f32_e32 v214, v214
	v_exp_f32_e32 v215, v215
	v_pk_add_f32 v[208:209], v[208:209], 1.0 op_sel_hi:[1,0]
	v_pk_add_f32 v[210:211], v[210:211], 1.0 op_sel_hi:[1,0]
	v_pk_add_f32 v[212:213], v[212:213], 1.0 op_sel_hi:[1,0]
	v_pk_add_f32 v[214:215], v[214:215], 1.0 op_sel_hi:[1,0]
	v_cvt_pk_bf16_f32 v132, v208, v209
	v_cvt_pk_bf16_f32 v133, v210, v211
	v_cvt_pk_bf16_f32 v134, v212, v213
	v_cvt_pk_bf16_f32 v135, v214, v215
	v_add_co_u32_e32 v136, vcc, 0x108000, v136
	v_addc_co_u32_e32 v137, vcc, 0, v137, vcc
	global_store_dwordx4 v[136:137], v[132:135], off
